# v16 + nt (streaming) policy on the SwiGLU epilogue stores of the gate/up GEMMs (ACT output), to keep weights/activations in the memory-side cache
# speedup vs baseline: 1.0175x; 1.0175x over previous
; __device__ __forceinline__ unsigned cvt_pk_bf16(float lo, float hi) { unsigned r; asm volatile("v_cvt_pk_bf16_f32 %0, %1, %2" : "=v"(r) : "v"(lo), "v"(hi)); return r; }
; __device__ __forceinline__ unsigned cvt_pk_bf16(float lo, float hi) { unsigned r; asm volatile("v_cvt_pk_bf16_f32 %0, %1, %2" : "=v"(r) : "v"(lo), "v"(hi)); return r; }
; __device__ __forceinline__ float ssq_rstd(const ssq_t* ssq, int row) { return __builtin_amdgcn_rsqf((float)ssq[row] * (SSQ_UNFIX * RMS_INV_D) + RMS_EPS); }
;     __device__ __forceinline__ void operator()(const f32x4 (&acc)[2][2][4][2], const Unit& u, int wr, int wc, int fr, int fq) const {
;         const int row0 = u.pm * BM + wr * 64 + fr, col0 = u.pn * HALF + wc * 32 + 8 * fq;
;         float rs[2][4];
; #pragma unroll
;         for (int ai = 0; ai < 2; ++ai)
; #pragma unroll
;             for (int m = 0; m < 4; ++m) rs[ai][m] = ssq_rstd(ssq, row0 + ai * HALF + m * 16);
; #pragma unroll
;         for (int ai = 0; ai < 2; ++ai)
; #pragma unroll
;             for (int m = 0; m < 4; ++m) { const int row = row0 + ai * HALF + m * 16; bf16_t* rowp = O + (size_t)row * ldc + col0; float a[8];
; #pragma unroll
;                 for (int n = 0; n < 2; ++n)
; #pragma unroll
;                     for (int i = 0; i < 4; i += 2) {
;                         const f32x2 r2 = {rs[ai][m], rs[ai][m]};
;                         const f32x2 g = (f32x2){acc[ai][0][m][n][i], acc[ai][0][m][n][i + 1]} * r2, up = (f32x2){acc[ai][1][m][n][i], acc[ai][1][m][n][i + 1]} * r2;
;                         const f32x2 t = g * (f32x2){-1.4426950408889634f, -1.4426950408889634f};
;                         const f32x2 d = (f32x2){__builtin_amdgcn_exp2f(t.x), __builtin_amdgcn_exp2f(t.y)} + (f32x2){1.0f, 1.0f};
;                         const f32x2 o2 = (g * up) * (f32x2){__builtin_amdgcn_rcpf(d.x), __builtin_amdgcn_rcpf(d.y)};
;                         a[4 * n + i] = o2.x; a[4 * n + i + 1] = o2.y; }
;                 u32x4 w; w.x = cvt_pk_bf16(a[0], a[1]); w.y = cvt_pk_bf16(a[2], a[3]); w.z = cvt_pk_bf16(a[4], a[5]); w.w = cvt_pk_bf16(a[6], a[7]);
;                 *(u32x4*)rowp = w; }
.LBB0_1129:
	v_lshl_add_u32 v168, s20, 8, v147
	v_ashrrev_i32_e32 v169, 31, v168
	v_or_b32_e32 v166, 16, v168
	v_or_b32_e32 v160, 32, v168
	v_or_b32_e32 v156, 48, v168
	v_lshl_add_u64 v[148:149], v[168:169], 3, s[4:5]
	v_ashrrev_i32_e32 v167, 31, v166
	v_ashrrev_i32_e32 v161, 31, v160
	v_ashrrev_i32_e32 v157, 31, v156
	v_lshl_add_u64 v[162:163], v[166:167], 3, s[4:5]
	v_lshl_add_u64 v[170:171], v[160:161], 3, s[4:5]
	global_load_dwordx2 v[172:173], v[148:149], off
	global_load_dwordx2 v[174:175], v[148:149], off offset:1024
	global_load_dwordx2 v[176:177], v[148:149], off offset:1152
	global_load_dwordx2 v[178:179], v[148:149], off offset:1280
	v_lshl_add_u64 v[180:181], v[156:157], 3, s[4:5]
	global_load_dwordx2 v[182:183], v[162:163], off
	s_nop 0
	global_load_dwordx2 v[170:171], v[170:171], off
	s_nop 0
	global_load_dwordx2 v[180:181], v[180:181], off
	s_nop 0
	global_load_dwordx2 v[148:149], v[148:149], off offset:1408
	v_add_u32_e32 v165, 0x80, v168
	v_add_u32_e32 v163, 0x90, v168
	v_add_u32_e32 v161, 0xa0, v168
	s_andn2_b64 vcc, exec, s[0:1]
	s_mov_b64 s[0:1], -1
	s_waitcnt vmcnt(0)
	v_ffbh_u32_e32 v146, v173
	v_min_u32_e32 v146, 32, v146
	v_lshlrev_b64 v[172:173], v146, v[172:173]
	v_ffbh_u32_e32 v158, v171
	v_min_u32_e32 v158, 32, v158
	v_min_u32_e32 v169, 1, v172
	v_lshlrev_b64 v[170:171], v158, v[170:171]
	v_or_b32_e32 v169, v173, v169
	v_min_u32_e32 v170, 1, v170
	v_cvt_f32_u32_e32 v169, v169
	v_ffbh_u32_e32 v150, v175
	v_ffbh_u32_e32 v152, v177
	v_ffbh_u32_e32 v154, v179
	v_ffbh_u32_e32 v162, v181
	v_or_b32_e32 v170, v171, v170
	v_min_u32_e32 v150, 32, v150
	v_min_u32_e32 v152, 32, v152
	v_min_u32_e32 v154, 32, v154
	v_min_u32_e32 v162, 32, v162
	v_cvt_f32_u32_e32 v170, v170
	v_sub_u32_e32 v146, 32, v146
	v_lshlrev_b64 v[174:175], v150, v[174:175]
	v_lshlrev_b64 v[176:177], v152, v[176:177]
	v_lshlrev_b64 v[178:179], v154, v[178:179]
	v_lshlrev_b64 v[180:181], v162, v[180:181]
	v_min_u32_e32 v172, 1, v174
	v_min_u32_e32 v174, 1, v176
	v_min_u32_e32 v176, 1, v178
	v_min_u32_e32 v178, 1, v180
	v_ldexp_f32 v146, v169, v146
	v_sub_u32_e32 v158, 32, v158
	v_or_b32_e32 v171, v181, v178
	v_fmamk_f32 v146, v146, 0x2d800000, v159
	v_cvt_f32_u32_e32 v171, v171
	v_ldexp_f32 v158, v170, v158
	v_rsq_f32_e32 v170, v146
	v_or_b32_e32 v172, v175, v172
	v_or_b32_e32 v174, v177, v174
	v_or_b32_e32 v175, v179, v176
	v_pk_mul_f32 v[122:123], v[122:123], v[170:171] op_sel_hi:[1,0]
	v_pk_mul_f32 v[124:125], v[124:125], v[170:171] op_sel_hi:[1,0]
	v_pk_mul_f32 v[176:177], v[122:123], s[10:11] op_sel_hi:[1,0]
	v_pk_mul_f32 v[178:179], v[124:125], s[10:11] op_sel_hi:[1,0]
	v_exp_f32_e32 v176, v176
	v_exp_f32_e32 v177, v177
	v_exp_f32_e32 v178, v178
	v_exp_f32_e32 v179, v179
	v_ffbh_u32_e32 v157, v183
	v_pk_add_f32 v[176:177], v[176:177], 1.0 op_sel_hi:[1,0]
	v_min_u32_e32 v157, 32, v157
	v_pk_mul_f32 v[126:127], v[126:127], v[170:171] op_sel_hi:[1,0]
	v_rcp_f32_e32 v176, v176
	v_rcp_f32_e32 v177, v177
	v_lshlrev_b64 v[182:183], v157, v[182:183]
	v_pk_mul_f32 v[122:123], v[122:123], v[126:127]
	v_pk_mul_f32 v[126:127], v[128:129], v[170:171] op_sel_hi:[1,0]
	v_pk_add_f32 v[128:129], v[178:179], 1.0 op_sel_hi:[1,0]
	v_min_u32_e32 v173, 1, v182
	v_rcp_f32_e32 v128, v128
	v_rcp_f32_e32 v129, v129
	v_or_b32_e32 v173, v183, v173
	v_pk_mul_f32 v[114:115], v[114:115], v[170:171] op_sel_hi:[1,0]
	v_cvt_f32_u32_e32 v173, v173
	v_pk_mul_f32 v[122:123], v[122:123], v[176:177]
	v_pk_mul_f32 v[176:177], v[114:115], s[10:11] op_sel_hi:[1,0]
	v_pk_mul_f32 v[124:125], v[124:125], v[126:127]
	v_exp_f32_e32 v176, v176
	v_exp_f32_e32 v177, v177
	v_pk_mul_f32 v[116:117], v[116:117], v[170:171] op_sel_hi:[1,0]
	v_ffbh_u32_e32 v167, v149
	v_cvt_f32_u32_e32 v172, v172
	v_pk_mul_f32 v[124:125], v[124:125], v[128:129]
	v_pk_mul_f32 v[128:129], v[116:117], s[10:11] op_sel_hi:[1,0]
	v_min_u32_e32 v167, 32, v167
	v_sub_u32_e32 v157, 32, v157
	v_exp_f32_e32 v128, v128
	v_exp_f32_e32 v129, v129
	v_lshlrev_b64 v[148:149], v167, v[148:149]
	v_ldexp_f32 v157, v173, v157
	v_sub_u32_e32 v150, 32, v150
	v_min_u32_e32 v148, 1, v148
	v_fmamk_f32 v146, v157, 0x2d800000, v159
	v_pk_mul_f32 v[118:119], v[118:119], v[170:171] op_sel_hi:[1,0]
	v_pk_add_f32 v[126:127], v[176:177], 1.0 op_sel_hi:[1,0]
	v_cvt_f32_u32_e32 v174, v174
	v_cvt_f32_u32_e32 v175, v175
	v_ldexp_f32 v150, v172, v150
	v_rsq_f32_e32 v172, v146
	v_or_b32_e32 v146, v149, v148
	v_pk_mul_f32 v[114:115], v[114:115], v[118:119]
	v_rcp_f32_e32 v118, v126
	v_rcp_f32_e32 v119, v127
	v_cvt_f32_u32_e32 v146, v146
	v_pk_add_f32 v[126:127], v[128:129], 1.0 op_sel_hi:[1,0]
	v_sub_u32_e32 v152, 32, v152
	v_rcp_f32_e32 v126, v126
	v_rcp_f32_e32 v127, v127
	v_sub_u32_e32 v154, 32, v154
	v_sub_u32_e32 v162, 32, v162
	v_ldexp_f32 v152, v174, v152
	v_ldexp_f32 v154, v175, v154
	v_sub_u32_e32 v148, 32, v167
	v_lshl_or_b32 v174, s63, 7, v153
	v_pk_mul_f32 v[118:119], v[114:115], v[118:119]
	v_pk_mul_f32 v[114:115], v[120:121], v[170:171] op_sel_hi:[1,0]
	v_ldexp_f32 v162, v171, v162
	v_fmamk_f32 v150, v150, 0x2d800000, v159
	v_fmamk_f32 v169, v154, 0x2d800000, v159
	v_fmamk_f32 v157, v158, 0x2d800000, v159
	v_ldexp_f32 v146, v146, v148
	v_ashrrev_i32_e32 v175, 31, v174
	v_mov_b64_e32 v[148:149], s[38:39]
	v_pk_mul_f32 v[114:115], v[116:117], v[114:115]
	v_fmamk_f32 v158, v162, 0x2d800000, v159
	v_rsq_f32_e32 v154, v150
	v_rsq_f32_e32 v162, v157
	v_rsq_f32_e32 v150, v169
	v_add_u32_e32 v157, 0xb0, v168
	v_mad_i64_i32 v[168:169], s[22:23], v168, s62, v[148:149]
	v_pk_mul_f32 v[120:121], v[114:115], v[126:127]
	v_lshlrev_b64 v[114:115], 1, v[174:175]
	v_lshl_add_u64 v[126:127], v[168:169], 0, v[114:115]
	v_cvt_pk_bf16_f32 v116, v122, v123
; __device__ __forceinline__ unsigned cvt_pk_bf16(float lo, float hi) { unsigned r; asm volatile("v_cvt_pk_bf16_f32 %0, %1, %2" : "=v"(r) : "v"(lo), "v"(hi)); return r; }
; __device__ __forceinline__ unsigned cvt_pk_bf16(float lo, float hi) { unsigned r; asm volatile("v_cvt_pk_bf16_f32 %0, %1, %2" : "=v"(r) : "v"(lo), "v"(hi)); return r; }
;     __device__ __forceinline__ void operator()(const f32x4 (&acc)[2][2][4][2], const Unit& u, int wr, int wc, int fr, int fq) const {
;     ...
;         for (int ai = 0; ai < 2; ++ai)
; #pragma unroll
;             for (int m = 0; m < 4; ++m) { const int row = row0 + ai * HALF + m * 16; bf16_t* rowp = O + (size_t)row * ldc + col0; float a[8];
; #pragma unroll
;                 for (int n = 0; n < 2; ++n)
; #pragma unroll
;                     for (int i = 0; i < 4; i += 2) {
;                         const f32x2 r2 = {rs[ai][m], rs[ai][m]};
;                         const f32x2 g = (f32x2){acc[ai][0][m][n][i], acc[ai][0][m][n][i + 1]} * r2, up = (f32x2){acc[ai][1][m][n][i], acc[ai][1][m][n][i + 1]} * r2;
;                         const f32x2 t = g * (f32x2){-1.4426950408889634f, -1.4426950408889634f};
;                         const f32x2 d = (f32x2){__builtin_amdgcn_exp2f(t.x), __builtin_amdgcn_exp2f(t.y)} + (f32x2){1.0f, 1.0f};
;                         const f32x2 o2 = (g * up) * (f32x2){__builtin_amdgcn_rcpf(d.x), __builtin_amdgcn_rcpf(d.y)};
;                         a[4 * n + i] = o2.x; a[4 * n + i + 1] = o2.y; }
;                 u32x4 w; w.x = cvt_pk_bf16(a[0], a[1]); w.y = cvt_pk_bf16(a[2], a[3]); w.z = cvt_pk_bf16(a[4], a[5]); w.w = cvt_pk_bf16(a[6], a[7]);
;                 *(u32x4*)rowp = w; }
	v_cvt_pk_bf16_f32 v117, v124, v125
	v_pk_mul_f32 v[106:107], v[106:107], v[172:173] op_sel_hi:[1,0]
	v_cvt_pk_bf16_f32 v118, v118, v119
	v_cvt_pk_bf16_f32 v119, v120, v121
	global_store_dwordx4 v[126:127], v[116:119], off nt
	v_pk_mul_f32 v[108:109], v[108:109], v[172:173] op_sel_hi:[1,0]
	v_pk_mul_f32 v[110:111], v[110:111], v[172:173] op_sel_hi:[1,0]
	v_pk_mul_f32 v[116:117], v[106:107], s[10:11] op_sel_hi:[1,0]
	v_pk_mul_f32 v[120:121], v[108:109], s[10:11] op_sel_hi:[1,0]
	v_exp_f32_e32 v116, v116
	v_exp_f32_e32 v117, v117
	v_exp_f32_e32 v120, v120
	v_exp_f32_e32 v121, v121
	v_pk_mul_f32 v[106:107], v[106:107], v[110:111]
	v_pk_add_f32 v[116:117], v[116:117], 1.0 op_sel_hi:[1,0]
	v_pk_mul_f32 v[110:111], v[112:113], v[172:173] op_sel_hi:[1,0]
	v_rcp_f32_e32 v116, v116
	v_rcp_f32_e32 v117, v117
	v_pk_add_f32 v[112:113], v[120:121], 1.0 op_sel_hi:[1,0]
	v_pk_mul_f32 v[98:99], v[98:99], v[172:173] op_sel_hi:[1,0]
	v_rcp_f32_e32 v112, v112
	v_rcp_f32_e32 v113, v113
	v_pk_mul_f32 v[106:107], v[106:107], v[116:117]
	v_pk_mul_f32 v[116:117], v[98:99], s[10:11] op_sel_hi:[1,0]
	v_pk_mul_f32 v[108:109], v[108:109], v[110:111]
	v_exp_f32_e32 v116, v116
	v_exp_f32_e32 v117, v117
	v_pk_mul_f32 v[100:101], v[100:101], v[172:173] op_sel_hi:[1,0]
	v_pk_mul_f32 v[108:109], v[108:109], v[112:113]
	v_pk_mul_f32 v[112:113], v[100:101], s[10:11] op_sel_hi:[1,0]
	v_pk_mul_f32 v[102:103], v[102:103], v[172:173] op_sel_hi:[1,0]
	v_exp_f32_e32 v112, v112
	v_exp_f32_e32 v113, v113
	v_pk_add_f32 v[110:111], v[116:117], 1.0 op_sel_hi:[1,0]
	v_pk_mul_f32 v[98:99], v[98:99], v[102:103]
	v_rcp_f32_e32 v102, v110
	v_rcp_f32_e32 v103, v111
	v_pk_add_f32 v[110:111], v[112:113], 1.0 op_sel_hi:[1,0]
	v_mad_i64_i32 v[118:119], s[22:23], v166, s62, v[148:149]
	v_rcp_f32_e32 v110, v110
	v_rcp_f32_e32 v111, v111
	v_pk_mul_f32 v[102:103], v[98:99], v[102:103]
	v_pk_mul_f32 v[98:99], v[104:105], v[172:173] op_sel_hi:[1,0]
	v_pk_mul_f32 v[90:91], v[90:91], v[162:163] op_sel_hi:[1,0]
	v_pk_mul_f32 v[98:99], v[100:101], v[98:99]
	v_pk_mul_f32 v[92:93], v[92:93], v[162:163] op_sel_hi:[1,0]
	v_pk_mul_f32 v[104:105], v[98:99], v[110:111]
	v_lshl_add_u64 v[110:111], v[118:119], 0, v[114:115]
	v_cvt_pk_bf16_f32 v98, v106, v107
	v_cvt_pk_bf16_f32 v99, v108, v109
	v_cvt_pk_bf16_f32 v100, v102, v103
	v_cvt_pk_bf16_f32 v101, v104, v105
	global_store_dwordx4 v[110:111], v[98:101], off nt
	v_pk_mul_f32 v[102:103], v[92:93], s[10:11] op_sel_hi:[1,0]
	v_pk_mul_f32 v[94:95], v[94:95], v[162:163] op_sel_hi:[1,0]
	v_pk_mul_f32 v[98:99], v[90:91], s[10:11] op_sel_hi:[1,0]
	v_exp_f32_e32 v102, v102
	v_exp_f32_e32 v98, v98
	v_exp_f32_e32 v99, v99
	v_exp_f32_e32 v103, v103
	v_pk_mul_f32 v[90:91], v[90:91], v[94:95]
	v_pk_mul_f32 v[94:95], v[96:97], v[162:163] op_sel_hi:[1,0]
	v_pk_add_f32 v[98:99], v[98:99], 1.0 op_sel_hi:[1,0]
	v_pk_add_f32 v[96:97], v[102:103], 1.0 op_sel_hi:[1,0]
	v_rcp_f32_e32 v98, v98
	v_rcp_f32_e32 v99, v99
	v_rcp_f32_e32 v96, v96
	v_rcp_f32_e32 v97, v97
	v_pk_mul_f32 v[82:83], v[82:83], v[162:163] op_sel_hi:[1,0]
	v_pk_mul_f32 v[90:91], v[90:91], v[98:99]
	v_pk_mul_f32 v[98:99], v[82:83], s[10:11] op_sel_hi:[1,0]
	v_pk_mul_f32 v[92:93], v[92:93], v[94:95]
	v_exp_f32_e32 v98, v98
	v_exp_f32_e32 v99, v99
	v_pk_mul_f32 v[84:85], v[84:85], v[162:163] op_sel_hi:[1,0]
	v_pk_mul_f32 v[92:93], v[92:93], v[96:97]
	v_pk_mul_f32 v[96:97], v[84:85], s[10:11] op_sel_hi:[1,0]
	v_pk_mul_f32 v[86:87], v[86:87], v[162:163] op_sel_hi:[1,0]
	v_exp_f32_e32 v96, v96
	v_exp_f32_e32 v97, v97
	v_pk_add_f32 v[94:95], v[98:99], 1.0 op_sel_hi:[1,0]
	v_pk_mul_f32 v[82:83], v[82:83], v[86:87]
	v_rcp_f32_e32 v86, v94
	v_rcp_f32_e32 v87, v95
	v_pk_add_f32 v[94:95], v[96:97], 1.0 op_sel_hi:[1,0]
	v_rsq_f32_e32 v158, v158
	v_rcp_f32_e32 v94, v94
	v_rcp_f32_e32 v95, v95
	v_pk_mul_f32 v[86:87], v[82:83], v[86:87]
	v_pk_mul_f32 v[82:83], v[88:89], v[162:163] op_sel_hi:[1,0]
	v_mad_i64_i32 v[100:101], s[22:23], v160, s62, v[148:149]
	v_pk_mul_f32 v[82:83], v[84:85], v[82:83]
	v_pk_mul_f32 v[74:75], v[74:75], v[158:159] op_sel_hi:[1,0]
	v_pk_mul_f32 v[88:89], v[82:83], v[94:95]
	v_lshl_add_u64 v[94:95], v[100:101], 0, v[114:115]
	v_cvt_pk_bf16_f32 v82, v90, v91
	v_cvt_pk_bf16_f32 v83, v92, v93
	v_cvt_pk_bf16_f32 v84, v86, v87
	v_cvt_pk_bf16_f32 v85, v88, v89
	global_store_dwordx4 v[94:95], v[82:85], off nt
	v_pk_mul_f32 v[76:77], v[76:77], v[158:159] op_sel_hi:[1,0]
	v_pk_mul_f32 v[78:79], v[78:79], v[158:159] op_sel_hi:[1,0]
	v_pk_mul_f32 v[82:83], v[74:75], s[10:11] op_sel_hi:[1,0]
	v_pk_mul_f32 v[86:87], v[76:77], s[10:11] op_sel_hi:[1,0]
	v_exp_f32_e32 v82, v82
	v_exp_f32_e32 v83, v83
	v_exp_f32_e32 v86, v86
	v_exp_f32_e32 v87, v87
	v_pk_mul_f32 v[74:75], v[74:75], v[78:79]
	v_pk_add_f32 v[82:83], v[82:83], 1.0 op_sel_hi:[1,0]
	v_pk_mul_f32 v[78:79], v[80:81], v[158:159] op_sel_hi:[1,0]
	v_rcp_f32_e32 v82, v82
	v_rcp_f32_e32 v83, v83
	v_pk_add_f32 v[80:81], v[86:87], 1.0 op_sel_hi:[1,0]
	v_pk_mul_f32 v[62:63], v[62:63], v[158:159] op_sel_hi:[1,0]
	v_rcp_f32_e32 v80, v80
	v_rcp_f32_e32 v81, v81
	v_pk_mul_f32 v[74:75], v[74:75], v[82:83]
	v_pk_mul_f32 v[82:83], v[62:63], s[10:11] op_sel_hi:[1,0]
	v_pk_mul_f32 v[76:77], v[76:77], v[78:79]
	v_exp_f32_e32 v82, v82
	v_exp_f32_e32 v83, v83
	v_pk_mul_f32 v[64:65], v[64:65], v[158:159] op_sel_hi:[1,0]
	v_pk_mul_f32 v[76:77], v[76:77], v[80:81]
	v_pk_mul_f32 v[80:81], v[64:65], s[10:11] op_sel_hi:[1,0]
	v_pk_mul_f32 v[70:71], v[70:71], v[158:159] op_sel_hi:[1,0]
	v_exp_f32_e32 v80, v80
	v_exp_f32_e32 v81, v81
	v_pk_add_f32 v[78:79], v[82:83], 1.0 op_sel_hi:[1,0]
	v_pk_mul_f32 v[62:63], v[62:63], v[70:71]
	v_rcp_f32_e32 v70, v78
	v_rcp_f32_e32 v71, v79
; __device__ __forceinline__ unsigned cvt_pk_bf16(float lo, float hi) { unsigned r; asm volatile("v_cvt_pk_bf16_f32 %0, %1, %2" : "=v"(r) : "v"(lo), "v"(hi)); return r; }
; __device__ __forceinline__ unsigned cvt_pk_bf16(float lo, float hi) { unsigned r; asm volatile("v_cvt_pk_bf16_f32 %0, %1, %2" : "=v"(r) : "v"(lo), "v"(hi)); return r; }
;     __device__ __forceinline__ void operator()(const f32x4 (&acc)[2][2][4][2], const Unit& u, int wr, int wc, int fr, int fq) const {
;     ...
;         for (int ai = 0; ai < 2; ++ai)
; #pragma unroll
;             for (int m = 0; m < 4; ++m) { const int row = row0 + ai * HALF + m * 16; bf16_t* rowp = O + (size_t)row * ldc + col0; float a[8];
; #pragma unroll
;                 for (int n = 0; n < 2; ++n)
; #pragma unroll
;                     for (int i = 0; i < 4; i += 2) {
;                         const f32x2 r2 = {rs[ai][m], rs[ai][m]};
;                         const f32x2 g = (f32x2){acc[ai][0][m][n][i], acc[ai][0][m][n][i + 1]} * r2, up = (f32x2){acc[ai][1][m][n][i], acc[ai][1][m][n][i + 1]} * r2;
;                         const f32x2 t = g * (f32x2){-1.4426950408889634f, -1.4426950408889634f};
;                         const f32x2 d = (f32x2){__builtin_amdgcn_exp2f(t.x), __builtin_amdgcn_exp2f(t.y)} + (f32x2){1.0f, 1.0f};
;                         const f32x2 o2 = (g * up) * (f32x2){__builtin_amdgcn_rcpf(d.x), __builtin_amdgcn_rcpf(d.y)};
;                         a[4 * n + i] = o2.x; a[4 * n + i + 1] = o2.y; }
;                 u32x4 w; w.x = cvt_pk_bf16(a[0], a[1]); w.y = cvt_pk_bf16(a[2], a[3]); w.z = cvt_pk_bf16(a[4], a[5]); w.w = cvt_pk_bf16(a[6], a[7]);
;                 *(u32x4*)rowp = w; }
	v_pk_add_f32 v[78:79], v[80:81], 1.0 op_sel_hi:[1,0]
	v_mad_i64_i32 v[84:85], s[22:23], v156, s62, v[148:149]
	v_rcp_f32_e32 v78, v78
	v_rcp_f32_e32 v79, v79
	v_pk_mul_f32 v[70:71], v[62:63], v[70:71]
	v_pk_mul_f32 v[62:63], v[72:73], v[158:159] op_sel_hi:[1,0]
	v_pk_mul_f32 v[58:59], v[58:59], v[154:155] op_sel_hi:[1,0]
	v_pk_mul_f32 v[62:63], v[64:65], v[62:63]
	v_pk_mul_f32 v[60:61], v[60:61], v[154:155] op_sel_hi:[1,0]
	v_pk_mul_f32 v[72:73], v[62:63], v[78:79]
	v_lshl_add_u64 v[78:79], v[84:85], 0, v[114:115]
	v_cvt_pk_bf16_f32 v62, v74, v75
	v_cvt_pk_bf16_f32 v63, v76, v77
	v_cvt_pk_bf16_f32 v64, v70, v71
	v_cvt_pk_bf16_f32 v65, v72, v73
	global_store_dwordx4 v[78:79], v[62:65], off nt
	v_pk_mul_f32 v[70:71], v[60:61], s[10:11] op_sel_hi:[1,0]
	v_pk_mul_f32 v[66:67], v[66:67], v[154:155] op_sel_hi:[1,0]
	v_pk_mul_f32 v[62:63], v[58:59], s[10:11] op_sel_hi:[1,0]
	v_exp_f32_e32 v70, v70
	v_exp_f32_e32 v62, v62
	v_exp_f32_e32 v63, v63
	v_exp_f32_e32 v71, v71
	v_pk_mul_f32 v[58:59], v[58:59], v[66:67]
	v_pk_mul_f32 v[50:51], v[50:51], v[154:155] op_sel_hi:[1,0]
	v_pk_add_f32 v[62:63], v[62:63], 1.0 op_sel_hi:[1,0]
	v_pk_add_f32 v[66:67], v[70:71], 1.0 op_sel_hi:[1,0]
	v_rcp_f32_e32 v62, v62
	v_rcp_f32_e32 v63, v63
	v_rcp_f32_e32 v66, v66
	v_rcp_f32_e32 v67, v67
	v_pk_mul_f32 v[52:53], v[52:53], v[154:155] op_sel_hi:[1,0]
	v_pk_mul_f32 v[58:59], v[58:59], v[62:63]
	v_pk_mul_f32 v[62:63], v[68:69], v[154:155] op_sel_hi:[1,0]
	v_pk_mul_f32 v[68:69], v[50:51], s[10:11] op_sel_hi:[1,0]
	v_pk_mul_f32 v[60:61], v[60:61], v[62:63]
	v_exp_f32_e32 v68, v68
	v_exp_f32_e32 v69, v69
	v_pk_mul_f32 v[60:61], v[60:61], v[66:67]
	v_pk_mul_f32 v[66:67], v[52:53], s[10:11] op_sel_hi:[1,0]
	v_pk_mul_f32 v[54:55], v[54:55], v[154:155] op_sel_hi:[1,0]
	v_exp_f32_e32 v66, v66
	v_exp_f32_e32 v67, v67
	v_pk_add_f32 v[62:63], v[68:69], 1.0 op_sel_hi:[1,0]
	v_pk_mul_f32 v[50:51], v[50:51], v[54:55]
	v_rcp_f32_e32 v54, v62
	v_rcp_f32_e32 v55, v63
	v_fmamk_f32 v152, v152, 0x2d800000, v159
	v_pk_add_f32 v[62:63], v[66:67], 1.0 op_sel_hi:[1,0]
	v_rsq_f32_e32 v152, v152
	v_rcp_f32_e32 v62, v62
	v_rcp_f32_e32 v63, v63
	v_pk_mul_f32 v[54:55], v[50:51], v[54:55]
	v_pk_mul_f32 v[50:51], v[56:57], v[154:155] op_sel_hi:[1,0]
	v_mad_i64_i32 v[64:65], s[22:23], v165, s62, v[148:149]
	v_pk_mul_f32 v[50:51], v[52:53], v[50:51]
	v_pk_mul_f32 v[42:43], v[42:43], v[152:153] op_sel_hi:[1,0]
	v_pk_mul_f32 v[56:57], v[50:51], v[62:63]
	v_lshl_add_u64 v[62:63], v[64:65], 0, v[114:115]
	v_cvt_pk_bf16_f32 v50, v58, v59
	v_cvt_pk_bf16_f32 v51, v60, v61
	v_cvt_pk_bf16_f32 v52, v54, v55
	v_cvt_pk_bf16_f32 v53, v56, v57
	global_store_dwordx4 v[62:63], v[50:53], off nt
	v_pk_mul_f32 v[44:45], v[44:45], v[152:153] op_sel_hi:[1,0]
	v_pk_mul_f32 v[46:47], v[46:47], v[152:153] op_sel_hi:[1,0]
	v_pk_mul_f32 v[50:51], v[42:43], s[10:11] op_sel_hi:[1,0]
	v_pk_mul_f32 v[54:55], v[44:45], s[10:11] op_sel_hi:[1,0]
	v_exp_f32_e32 v50, v50
	v_exp_f32_e32 v51, v51
	v_exp_f32_e32 v54, v54
	v_exp_f32_e32 v55, v55
	v_pk_mul_f32 v[42:43], v[42:43], v[46:47]
	v_pk_add_f32 v[50:51], v[50:51], 1.0 op_sel_hi:[1,0]
	v_pk_mul_f32 v[46:47], v[48:49], v[152:153] op_sel_hi:[1,0]
	v_rcp_f32_e32 v50, v50
	v_rcp_f32_e32 v51, v51
	v_pk_add_f32 v[48:49], v[54:55], 1.0 op_sel_hi:[1,0]
	v_pk_mul_f32 v[34:35], v[34:35], v[152:153] op_sel_hi:[1,0]
	v_rcp_f32_e32 v48, v48
	v_rcp_f32_e32 v49, v49
	v_pk_mul_f32 v[42:43], v[42:43], v[50:51]
	v_pk_mul_f32 v[50:51], v[34:35], s[10:11] op_sel_hi:[1,0]
	v_pk_mul_f32 v[44:45], v[44:45], v[46:47]
	v_exp_f32_e32 v50, v50
	v_exp_f32_e32 v51, v51
	v_pk_mul_f32 v[36:37], v[36:37], v[152:153] op_sel_hi:[1,0]
	v_pk_mul_f32 v[44:45], v[44:45], v[48:49]
	v_pk_mul_f32 v[48:49], v[36:37], s[10:11] op_sel_hi:[1,0]
	v_pk_mul_f32 v[38:39], v[38:39], v[152:153] op_sel_hi:[1,0]
	v_exp_f32_e32 v48, v48
	v_exp_f32_e32 v49, v49
	v_pk_add_f32 v[46:47], v[50:51], 1.0 op_sel_hi:[1,0]
	v_pk_mul_f32 v[34:35], v[34:35], v[38:39]
	v_rcp_f32_e32 v38, v46
	v_rcp_f32_e32 v39, v47
	v_pk_add_f32 v[46:47], v[48:49], 1.0 op_sel_hi:[1,0]
	v_mad_i64_i32 v[52:53], s[22:23], v163, s62, v[148:149]
	v_rcp_f32_e32 v46, v46
	v_rcp_f32_e32 v47, v47
	v_pk_mul_f32 v[38:39], v[34:35], v[38:39]
	v_pk_mul_f32 v[34:35], v[40:41], v[152:153] op_sel_hi:[1,0]
	v_pk_mul_f32 v[26:27], v[26:27], v[150:151] op_sel_hi:[1,0]
	v_pk_mul_f32 v[34:35], v[36:37], v[34:35]
	v_pk_mul_f32 v[28:29], v[28:29], v[150:151] op_sel_hi:[1,0]
	v_pk_mul_f32 v[40:41], v[34:35], v[46:47]
	v_lshl_add_u64 v[46:47], v[52:53], 0, v[114:115]
	v_cvt_pk_bf16_f32 v34, v42, v43
	v_cvt_pk_bf16_f32 v35, v44, v45
	v_cvt_pk_bf16_f32 v36, v38, v39
	v_cvt_pk_bf16_f32 v37, v40, v41
	global_store_dwordx4 v[46:47], v[34:37], off nt
	v_pk_mul_f32 v[38:39], v[28:29], s[10:11] op_sel_hi:[1,0]
	v_pk_mul_f32 v[30:31], v[30:31], v[150:151] op_sel_hi:[1,0]
	v_pk_mul_f32 v[34:35], v[26:27], s[10:11] op_sel_hi:[1,0]
	v_exp_f32_e32 v38, v38
	v_exp_f32_e32 v34, v34
	v_exp_f32_e32 v35, v35
	v_exp_f32_e32 v39, v39
	v_pk_mul_f32 v[26:27], v[26:27], v[30:31]
	v_pk_mul_f32 v[30:31], v[32:33], v[150:151] op_sel_hi:[1,0]
; __device__ __forceinline__ unsigned cvt_pk_bf16(float lo, float hi) { unsigned r; asm volatile("v_cvt_pk_bf16_f32 %0, %1, %2" : "=v"(r) : "v"(lo), "v"(hi)); return r; }
; __device__ __forceinline__ unsigned cvt_pk_bf16(float lo, float hi) { unsigned r; asm volatile("v_cvt_pk_bf16_f32 %0, %1, %2" : "=v"(r) : "v"(lo), "v"(hi)); return r; }
; #define PG8_BAR __builtin_amdgcn_s_barrier()
;     __device__ __forceinline__ void operator()(const f32x4 (&acc)[2][2][4][2], const Unit& u, int wr, int wc, int fr, int fq) const {
;     ...
;         for (int ai = 0; ai < 2; ++ai)
; #pragma unroll
;             for (int m = 0; m < 4; ++m) { const int row = row0 + ai * HALF + m * 16; bf16_t* rowp = O + (size_t)row * ldc + col0; float a[8];
; #pragma unroll
;                 for (int n = 0; n < 2; ++n)
; #pragma unroll
;                     for (int i = 0; i < 4; i += 2) {
;                         const f32x2 r2 = {rs[ai][m], rs[ai][m]};
;                         const f32x2 g = (f32x2){acc[ai][0][m][n][i], acc[ai][0][m][n][i + 1]} * r2, up = (f32x2){acc[ai][1][m][n][i], acc[ai][1][m][n][i + 1]} * r2;
;                         const f32x2 t = g * (f32x2){-1.4426950408889634f, -1.4426950408889634f};
;                         const f32x2 d = (f32x2){__builtin_amdgcn_exp2f(t.x), __builtin_amdgcn_exp2f(t.y)} + (f32x2){1.0f, 1.0f};
;                         const f32x2 o2 = (g * up) * (f32x2){__builtin_amdgcn_rcpf(d.x), __builtin_amdgcn_rcpf(d.y)};
;                         a[4 * n + i] = o2.x; a[4 * n + i + 1] = o2.y; }
;                 u32x4 w; w.x = cvt_pk_bf16(a[0], a[1]); w.y = cvt_pk_bf16(a[2], a[3]); w.z = cvt_pk_bf16(a[4], a[5]); w.w = cvt_pk_bf16(a[6], a[7]);
;                 *(u32x4*)rowp = w; }
; template <class Epi, class Sched, bool ALIGN_EPI = false, bool SP2 = false>
; __device__ __forceinline__ void gemm_phase(PG8_LAS unsigned char* lds, const Gemm g, const Sched& S, const Epi& E) {
;     ...
; #pragma unroll
;         for (int a = 0; a < 2; ++a)
; #pragma unroll
;             for (int b = 0; b < 2; ++b)
; #pragma unroll
;                 for (int m = 0; m < 4; ++m)
; #pragma unroll
;                     for (int n = 0; n < 2; ++n) { d64x2 z_; asm volatile("v_mov_b64 %0, 0\n\tv_mov_b64 %1, 0" : "=v"(z_.x), "=v"(z_.y)); acc[a][b][m][n] = __builtin_bit_cast(f32x4, z_); }
;         cur = nxt; cA = nA; cB = nB; ++ui;
;         if constexpr (ALIGN_EPI) { if (wr == 1) PG8_BAR; }
	v_pk_add_f32 v[34:35], v[34:35], 1.0 op_sel_hi:[1,0]
	v_pk_add_f32 v[32:33], v[38:39], 1.0 op_sel_hi:[1,0]
	v_rcp_f32_e32 v34, v34
	v_rcp_f32_e32 v35, v35
	v_rcp_f32_e32 v32, v32
	v_rcp_f32_e32 v33, v33
	v_pk_mul_f32 v[18:19], v[18:19], v[150:151] op_sel_hi:[1,0]
	v_pk_mul_f32 v[26:27], v[26:27], v[34:35]
	v_pk_mul_f32 v[34:35], v[18:19], s[10:11] op_sel_hi:[1,0]
	v_pk_mul_f32 v[28:29], v[28:29], v[30:31]
	v_exp_f32_e32 v34, v34
	v_exp_f32_e32 v35, v35
	v_pk_mul_f32 v[20:21], v[20:21], v[150:151] op_sel_hi:[1,0]
	v_pk_mul_f32 v[28:29], v[28:29], v[32:33]
	v_pk_mul_f32 v[32:33], v[20:21], s[10:11] op_sel_hi:[1,0]
	v_pk_mul_f32 v[22:23], v[22:23], v[150:151] op_sel_hi:[1,0]
	v_exp_f32_e32 v32, v32
	v_exp_f32_e32 v33, v33
	v_pk_add_f32 v[30:31], v[34:35], 1.0 op_sel_hi:[1,0]
	v_pk_mul_f32 v[18:19], v[18:19], v[22:23]
	v_rcp_f32_e32 v22, v30
	v_rcp_f32_e32 v23, v31
	v_fmamk_f32 v146, v146, 0x2d800000, v159
	v_pk_add_f32 v[30:31], v[32:33], 1.0 op_sel_hi:[1,0]
	v_rsq_f32_e32 v146, v146
	v_rcp_f32_e32 v30, v30
	v_rcp_f32_e32 v31, v31
	v_pk_mul_f32 v[22:23], v[18:19], v[22:23]
	v_pk_mul_f32 v[18:19], v[24:25], v[150:151] op_sel_hi:[1,0]
	v_mad_i64_i32 v[36:37], s[22:23], v161, s62, v[148:149]
	v_pk_mul_f32 v[18:19], v[20:21], v[18:19]
	v_pk_mul_f32 v[10:11], v[10:11], v[146:147] op_sel_hi:[1,0]
	v_pk_mul_f32 v[24:25], v[18:19], v[30:31]
	v_lshl_add_u64 v[30:31], v[36:37], 0, v[114:115]
	v_cvt_pk_bf16_f32 v18, v26, v27
	v_cvt_pk_bf16_f32 v19, v28, v29
	v_cvt_pk_bf16_f32 v20, v22, v23
	v_cvt_pk_bf16_f32 v21, v24, v25
	global_store_dwordx4 v[30:31], v[18:21], off nt
	v_pk_mul_f32 v[12:13], v[12:13], v[146:147] op_sel_hi:[1,0]
	v_pk_mul_f32 v[14:15], v[14:15], v[146:147] op_sel_hi:[1,0]
	v_pk_mul_f32 v[18:19], v[10:11], s[10:11] op_sel_hi:[1,0]
	v_pk_mul_f32 v[22:23], v[12:13], s[10:11] op_sel_hi:[1,0]
	v_exp_f32_e32 v18, v18
	v_exp_f32_e32 v19, v19
	v_exp_f32_e32 v22, v22
	v_exp_f32_e32 v23, v23
	v_pk_mul_f32 v[10:11], v[10:11], v[14:15]
	v_pk_add_f32 v[18:19], v[18:19], 1.0 op_sel_hi:[1,0]
	v_pk_mul_f32 v[14:15], v[16:17], v[146:147] op_sel_hi:[1,0]
	v_rcp_f32_e32 v18, v18
	v_rcp_f32_e32 v19, v19
	v_pk_add_f32 v[16:17], v[22:23], 1.0 op_sel_hi:[1,0]
	v_pk_mul_f32 v[2:3], v[2:3], v[146:147] op_sel_hi:[1,0]
	v_rcp_f32_e32 v16, v16
	v_rcp_f32_e32 v17, v17
	v_pk_mul_f32 v[10:11], v[10:11], v[18:19]
	v_pk_mul_f32 v[18:19], v[2:3], s[10:11] op_sel_hi:[1,0]
	v_pk_mul_f32 v[12:13], v[12:13], v[14:15]
	v_exp_f32_e32 v18, v18
	v_exp_f32_e32 v19, v19
	v_pk_mul_f32 v[4:5], v[4:5], v[146:147] op_sel_hi:[1,0]
	v_pk_mul_f32 v[12:13], v[12:13], v[16:17]
	v_pk_mul_f32 v[16:17], v[4:5], s[10:11] op_sel_hi:[1,0]
	v_pk_mul_f32 v[6:7], v[6:7], v[146:147] op_sel_hi:[1,0]
	v_exp_f32_e32 v16, v16
	v_exp_f32_e32 v17, v17
	v_pk_add_f32 v[14:15], v[18:19], 1.0 op_sel_hi:[1,0]
	v_pk_mul_f32 v[2:3], v[2:3], v[6:7]
	v_rcp_f32_e32 v6, v14
	v_rcp_f32_e32 v7, v15
	v_pk_add_f32 v[14:15], v[16:17], 1.0 op_sel_hi:[1,0]
	v_mad_i64_i32 v[20:21], s[22:23], v157, s62, v[148:149]
	v_rcp_f32_e32 v14, v14
	v_rcp_f32_e32 v15, v15
	v_pk_mul_f32 v[6:7], v[2:3], v[6:7]
	v_pk_mul_f32 v[2:3], v[8:9], v[146:147] op_sel_hi:[1,0]
	s_nop 0
	v_pk_mul_f32 v[2:3], v[4:5], v[2:3]
	s_nop 0
	v_pk_mul_f32 v[8:9], v[2:3], v[14:15]
	v_lshl_add_u64 v[14:15], v[20:21], 0, v[114:115]
	v_cvt_pk_bf16_f32 v2, v10, v11
	v_cvt_pk_bf16_f32 v3, v12, v13
	v_cvt_pk_bf16_f32 v4, v6, v7
	v_cvt_pk_bf16_f32 v5, v8, v9
	global_store_dwordx4 v[14:15], v[2:5], off nt
	s_cbranch_vccnz .LBB0_1122
	s_andn2_b64 vcc, exec, s[2:3]
	v_mov_b64 v[122:123], 0
	v_mov_b64 v[124:125], 0
	v_mov_b64 v[114:115], 0
	v_mov_b64 v[116:117], 0
	v_mov_b64 v[106:107], 0
	v_mov_b64 v[108:109], 0
	v_mov_b64 v[98:99], 0
	v_mov_b64 v[100:101], 0
	v_mov_b64 v[90:91], 0
	v_mov_b64 v[92:93], 0
	v_mov_b64 v[82:83], 0
	v_mov_b64 v[84:85], 0
	v_mov_b64 v[74:75], 0
	v_mov_b64 v[76:77], 0
	v_mov_b64 v[62:63], 0
	v_mov_b64 v[64:65], 0
	v_mov_b64 v[126:127], 0
	v_mov_b64 v[128:129], 0
	v_mov_b64 v[118:119], 0
	v_mov_b64 v[120:121], 0
	v_mov_b64 v[110:111], 0
	v_mov_b64 v[112:113], 0
	v_mov_b64 v[102:103], 0
	v_mov_b64 v[104:105], 0
	v_mov_b64 v[94:95], 0
	v_mov_b64 v[96:97], 0
	v_mov_b64 v[86:87], 0
	v_mov_b64 v[88:89], 0
	v_mov_b64 v[78:79], 0
	v_mov_b64 v[80:81], 0
	v_mov_b64 v[70:71], 0
	v_mov_b64 v[72:73], 0
	v_mov_b64 v[58:59], 0
	v_mov_b64 v[60:61], 0
	v_mov_b64 v[50:51], 0
	v_mov_b64 v[52:53], 0
	v_mov_b64 v[42:43], 0
	v_mov_b64 v[44:45], 0
	v_mov_b64 v[34:35], 0
	v_mov_b64 v[36:37], 0
	v_mov_b64 v[26:27], 0
	v_mov_b64 v[28:29], 0
	v_mov_b64 v[18:19], 0
	v_mov_b64 v[20:21], 0
	v_mov_b64 v[10:11], 0
	v_mov_b64 v[12:13], 0
	v_mov_b64 v[2:3], 0
	v_mov_b64 v[4:5], 0
	v_mov_b64 v[66:67], 0
	v_mov_b64 v[68:69], 0
	v_mov_b64 v[54:55], 0
	v_mov_b64 v[56:57], 0
	v_mov_b64 v[46:47], 0
	v_mov_b64 v[48:49], 0
	v_mov_b64 v[38:39], 0
	v_mov_b64 v[40:41], 0
	v_mov_b64 v[30:31], 0
	v_mov_b64 v[32:33], 0
	v_mov_b64 v[22:23], 0
	v_mov_b64 v[24:25], 0
	v_mov_b64 v[14:15], 0
	v_mov_b64 v[16:17], 0
	v_mov_b64 v[6:7], 0
	v_mov_b64 v[8:9], 0
	s_cbranch_vccnz .LBB0_1121
	s_barrier
	s_branch .LBB0_1121

; __device__ __forceinline__ unsigned cvt_pk_bf16(float lo, float hi) { unsigned r; asm volatile("v_cvt_pk_bf16_f32 %0, %1, %2" : "=v"(r) : "v"(lo), "v"(hi)); return r; }
; __device__ __forceinline__ unsigned cvt_pk_bf16(float lo, float hi) { unsigned r; asm volatile("v_cvt_pk_bf16_f32 %0, %1, %2" : "=v"(r) : "v"(lo), "v"(hi)); return r; }
; __device__ __forceinline__ float ssq_rstd(const ssq_t* ssq, int row) { return __builtin_amdgcn_rsqf((float)ssq[row] * (SSQ_UNFIX * RMS_INV_D) + RMS_EPS); }
;     __device__ __forceinline__ void operator()(const f32x4 (&acc)[2][2][4][2], const Unit& u, int wr, int wc, int fr, int fq) const {
;         const int row0 = u.pm * BM + wr * 64 + fr, col0 = u.pn * HALF + wc * 32 + 8 * fq;
;         float rs[2][4];
; #pragma unroll
;         for (int ai = 0; ai < 2; ++ai)
; #pragma unroll
;             for (int m = 0; m < 4; ++m) rs[ai][m] = ssq_rstd(ssq, row0 + ai * HALF + m * 16);
; #pragma unroll
;         for (int ai = 0; ai < 2; ++ai)
; #pragma unroll
;             for (int m = 0; m < 4; ++m) { const int row = row0 + ai * HALF + m * 16; bf16_t* rowp = O + (size_t)row * ldc + col0; float a[8];
; #pragma unroll
;                 for (int n = 0; n < 2; ++n)
; #pragma unroll
;                     for (int i = 0; i < 4; i += 2) {
;                         const f32x2 r2 = {rs[ai][m], rs[ai][m]};
;                         const f32x2 g = (f32x2){acc[ai][0][m][n][i], acc[ai][0][m][n][i + 1]} * r2, up = (f32x2){acc[ai][1][m][n][i], acc[ai][1][m][n][i + 1]} * r2;
;                         const f32x2 t = g * (f32x2){-1.4426950408889634f, -1.4426950408889634f};
;                         const f32x2 d = (f32x2){__builtin_amdgcn_exp2f(t.x), __builtin_amdgcn_exp2f(t.y)} + (f32x2){1.0f, 1.0f};
;                         const f32x2 o2 = (g * up) * (f32x2){__builtin_amdgcn_rcpf(d.x), __builtin_amdgcn_rcpf(d.y)};
;                         a[4 * n + i] = o2.x; a[4 * n + i + 1] = o2.y; }
;                 u32x4 w; w.x = cvt_pk_bf16(a[0], a[1]); w.y = cvt_pk_bf16(a[2], a[3]); w.z = cvt_pk_bf16(a[4], a[5]); w.w = cvt_pk_bf16(a[6], a[7]);
;                 *(u32x4*)rowp = w; }
.LBB0_1684:
	v_lshl_add_u32 v168, s20, 8, v147
	v_ashrrev_i32_e32 v169, 31, v168
	v_or_b32_e32 v166, 16, v168
	v_or_b32_e32 v160, 32, v168
	v_or_b32_e32 v156, 48, v168
	v_lshl_add_u64 v[148:149], v[168:169], 3, s[4:5]
	v_ashrrev_i32_e32 v167, 31, v166
	v_ashrrev_i32_e32 v161, 31, v160
	v_ashrrev_i32_e32 v157, 31, v156
	v_lshl_add_u64 v[162:163], v[166:167], 3, s[4:5]
	v_lshl_add_u64 v[170:171], v[160:161], 3, s[4:5]
	global_load_dwordx2 v[172:173], v[148:149], off
	global_load_dwordx2 v[174:175], v[148:149], off offset:1024
	global_load_dwordx2 v[176:177], v[148:149], off offset:1152
	global_load_dwordx2 v[178:179], v[148:149], off offset:1280
	v_lshl_add_u64 v[180:181], v[156:157], 3, s[4:5]
	global_load_dwordx2 v[182:183], v[162:163], off
	s_nop 0
	global_load_dwordx2 v[170:171], v[170:171], off
	s_nop 0
	global_load_dwordx2 v[180:181], v[180:181], off
	s_nop 0
	global_load_dwordx2 v[148:149], v[148:149], off offset:1408
	v_add_u32_e32 v165, 0x80, v168
	v_add_u32_e32 v163, 0x90, v168
	v_add_u32_e32 v161, 0xa0, v168
	s_andn2_b64 vcc, exec, s[0:1]
	s_mov_b64 s[0:1], -1
	s_waitcnt vmcnt(0)
	v_ffbh_u32_e32 v146, v173
	v_min_u32_e32 v146, 32, v146
	v_lshlrev_b64 v[172:173], v146, v[172:173]
	v_ffbh_u32_e32 v158, v171
	v_min_u32_e32 v158, 32, v158
	v_min_u32_e32 v169, 1, v172
	v_lshlrev_b64 v[170:171], v158, v[170:171]
	v_or_b32_e32 v169, v173, v169
	v_min_u32_e32 v170, 1, v170
	v_cvt_f32_u32_e32 v169, v169
	v_ffbh_u32_e32 v150, v175
	v_ffbh_u32_e32 v152, v177
	v_ffbh_u32_e32 v154, v179
	v_ffbh_u32_e32 v162, v181
	v_or_b32_e32 v170, v171, v170
	v_min_u32_e32 v150, 32, v150
	v_min_u32_e32 v152, 32, v152
	v_min_u32_e32 v154, 32, v154
	v_min_u32_e32 v162, 32, v162
	v_cvt_f32_u32_e32 v170, v170
	v_sub_u32_e32 v146, 32, v146
	v_lshlrev_b64 v[174:175], v150, v[174:175]
	v_lshlrev_b64 v[176:177], v152, v[176:177]
	v_lshlrev_b64 v[178:179], v154, v[178:179]
	v_lshlrev_b64 v[180:181], v162, v[180:181]
	v_min_u32_e32 v172, 1, v174
	v_min_u32_e32 v174, 1, v176
	v_min_u32_e32 v176, 1, v178
	v_min_u32_e32 v178, 1, v180
	v_ldexp_f32 v146, v169, v146
	v_sub_u32_e32 v158, 32, v158
	v_or_b32_e32 v171, v181, v178
	v_fmamk_f32 v146, v146, 0x2d800000, v159
	v_cvt_f32_u32_e32 v171, v171
	v_ldexp_f32 v158, v170, v158
	v_rsq_f32_e32 v170, v146
	v_or_b32_e32 v172, v175, v172
	v_or_b32_e32 v174, v177, v174
	v_or_b32_e32 v175, v179, v176
	v_pk_mul_f32 v[122:123], v[122:123], v[170:171] op_sel_hi:[1,0]
	v_pk_mul_f32 v[124:125], v[124:125], v[170:171] op_sel_hi:[1,0]
	v_pk_mul_f32 v[176:177], v[122:123], s[10:11] op_sel_hi:[1,0]
	v_pk_mul_f32 v[178:179], v[124:125], s[10:11] op_sel_hi:[1,0]
	v_exp_f32_e32 v176, v176
	v_exp_f32_e32 v177, v177
	v_exp_f32_e32 v178, v178
	v_exp_f32_e32 v179, v179
	v_ffbh_u32_e32 v157, v183
	v_pk_add_f32 v[176:177], v[176:177], 1.0 op_sel_hi:[1,0]
	v_min_u32_e32 v157, 32, v157
	v_pk_mul_f32 v[126:127], v[126:127], v[170:171] op_sel_hi:[1,0]
	v_rcp_f32_e32 v176, v176
	v_rcp_f32_e32 v177, v177
	v_lshlrev_b64 v[182:183], v157, v[182:183]
	v_pk_mul_f32 v[122:123], v[122:123], v[126:127]
	v_pk_mul_f32 v[126:127], v[128:129], v[170:171] op_sel_hi:[1,0]
	v_pk_add_f32 v[128:129], v[178:179], 1.0 op_sel_hi:[1,0]
	v_min_u32_e32 v173, 1, v182
	v_rcp_f32_e32 v128, v128
	v_rcp_f32_e32 v129, v129
	v_or_b32_e32 v173, v183, v173
	v_pk_mul_f32 v[114:115], v[114:115], v[170:171] op_sel_hi:[1,0]
	v_cvt_f32_u32_e32 v173, v173
	v_pk_mul_f32 v[122:123], v[122:123], v[176:177]
	v_pk_mul_f32 v[176:177], v[114:115], s[10:11] op_sel_hi:[1,0]
	v_pk_mul_f32 v[124:125], v[124:125], v[126:127]
	v_exp_f32_e32 v176, v176
	v_exp_f32_e32 v177, v177
	v_pk_mul_f32 v[116:117], v[116:117], v[170:171] op_sel_hi:[1,0]
	v_ffbh_u32_e32 v167, v149
	v_cvt_f32_u32_e32 v172, v172
	v_pk_mul_f32 v[124:125], v[124:125], v[128:129]
	v_pk_mul_f32 v[128:129], v[116:117], s[10:11] op_sel_hi:[1,0]
	v_min_u32_e32 v167, 32, v167
	v_sub_u32_e32 v157, 32, v157
	v_exp_f32_e32 v128, v128
	v_exp_f32_e32 v129, v129
	v_lshlrev_b64 v[148:149], v167, v[148:149]
	v_ldexp_f32 v157, v173, v157
	v_sub_u32_e32 v150, 32, v150
	v_min_u32_e32 v148, 1, v148
	v_fmamk_f32 v146, v157, 0x2d800000, v159
	v_pk_mul_f32 v[118:119], v[118:119], v[170:171] op_sel_hi:[1,0]
	v_pk_add_f32 v[126:127], v[176:177], 1.0 op_sel_hi:[1,0]
	v_cvt_f32_u32_e32 v174, v174
	v_cvt_f32_u32_e32 v175, v175
	v_ldexp_f32 v150, v172, v150
	v_rsq_f32_e32 v172, v146
	v_or_b32_e32 v146, v149, v148
	v_pk_mul_f32 v[114:115], v[114:115], v[118:119]
	v_rcp_f32_e32 v118, v126
	v_rcp_f32_e32 v119, v127
	v_cvt_f32_u32_e32 v146, v146
	v_pk_add_f32 v[126:127], v[128:129], 1.0 op_sel_hi:[1,0]
	v_sub_u32_e32 v152, 32, v152
	v_rcp_f32_e32 v126, v126
	v_rcp_f32_e32 v127, v127
	v_sub_u32_e32 v154, 32, v154
	v_sub_u32_e32 v162, 32, v162
	v_ldexp_f32 v152, v174, v152
	v_ldexp_f32 v154, v175, v154
	v_sub_u32_e32 v148, 32, v167
	v_lshl_or_b32 v174, s47, 7, v153
	v_pk_mul_f32 v[118:119], v[114:115], v[118:119]
	v_pk_mul_f32 v[114:115], v[120:121], v[170:171] op_sel_hi:[1,0]
	v_ldexp_f32 v162, v171, v162
	v_fmamk_f32 v150, v150, 0x2d800000, v159
	v_fmamk_f32 v169, v154, 0x2d800000, v159
	v_fmamk_f32 v157, v158, 0x2d800000, v159
	v_ldexp_f32 v146, v146, v148
	v_ashrrev_i32_e32 v175, 31, v174
	v_mov_b64_e32 v[148:149], s[38:39]
	v_pk_mul_f32 v[114:115], v[116:117], v[114:115]
	v_fmamk_f32 v158, v162, 0x2d800000, v159
	v_rsq_f32_e32 v154, v150
	v_rsq_f32_e32 v162, v157
	v_rsq_f32_e32 v150, v169
	v_add_u32_e32 v157, 0xb0, v168
	v_mad_i64_i32 v[168:169], s[22:23], v168, s46, v[148:149]
	v_pk_mul_f32 v[120:121], v[114:115], v[126:127]
	v_lshlrev_b64 v[114:115], 1, v[174:175]
	v_lshl_add_u64 v[126:127], v[168:169], 0, v[114:115]
	v_cvt_pk_bf16_f32 v116, v122, v123
; __device__ __forceinline__ unsigned cvt_pk_bf16(float lo, float hi) { unsigned r; asm volatile("v_cvt_pk_bf16_f32 %0, %1, %2" : "=v"(r) : "v"(lo), "v"(hi)); return r; }
; __device__ __forceinline__ unsigned cvt_pk_bf16(float lo, float hi) { unsigned r; asm volatile("v_cvt_pk_bf16_f32 %0, %1, %2" : "=v"(r) : "v"(lo), "v"(hi)); return r; }
;     __device__ __forceinline__ void operator()(const f32x4 (&acc)[2][2][4][2], const Unit& u, int wr, int wc, int fr, int fq) const {
;     ...
;         for (int ai = 0; ai < 2; ++ai)
; #pragma unroll
;             for (int m = 0; m < 4; ++m) { const int row = row0 + ai * HALF + m * 16; bf16_t* rowp = O + (size_t)row * ldc + col0; float a[8];
; #pragma unroll
;                 for (int n = 0; n < 2; ++n)
; #pragma unroll
;                     for (int i = 0; i < 4; i += 2) {
;                         const f32x2 r2 = {rs[ai][m], rs[ai][m]};
;                         const f32x2 g = (f32x2){acc[ai][0][m][n][i], acc[ai][0][m][n][i + 1]} * r2, up = (f32x2){acc[ai][1][m][n][i], acc[ai][1][m][n][i + 1]} * r2;
;                         const f32x2 t = g * (f32x2){-1.4426950408889634f, -1.4426950408889634f};
;                         const f32x2 d = (f32x2){__builtin_amdgcn_exp2f(t.x), __builtin_amdgcn_exp2f(t.y)} + (f32x2){1.0f, 1.0f};
;                         const f32x2 o2 = (g * up) * (f32x2){__builtin_amdgcn_rcpf(d.x), __builtin_amdgcn_rcpf(d.y)};
;                         a[4 * n + i] = o2.x; a[4 * n + i + 1] = o2.y; }
;                 u32x4 w; w.x = cvt_pk_bf16(a[0], a[1]); w.y = cvt_pk_bf16(a[2], a[3]); w.z = cvt_pk_bf16(a[4], a[5]); w.w = cvt_pk_bf16(a[6], a[7]);
;                 *(u32x4*)rowp = w; }
	v_cvt_pk_bf16_f32 v117, v124, v125
	v_pk_mul_f32 v[106:107], v[106:107], v[172:173] op_sel_hi:[1,0]
	v_cvt_pk_bf16_f32 v118, v118, v119
	v_cvt_pk_bf16_f32 v119, v120, v121
	global_store_dwordx4 v[126:127], v[116:119], off nt
	v_pk_mul_f32 v[108:109], v[108:109], v[172:173] op_sel_hi:[1,0]
	v_pk_mul_f32 v[110:111], v[110:111], v[172:173] op_sel_hi:[1,0]
	v_pk_mul_f32 v[116:117], v[106:107], s[10:11] op_sel_hi:[1,0]
	v_pk_mul_f32 v[120:121], v[108:109], s[10:11] op_sel_hi:[1,0]
	v_exp_f32_e32 v116, v116
	v_exp_f32_e32 v117, v117
	v_exp_f32_e32 v120, v120
	v_exp_f32_e32 v121, v121
	v_pk_mul_f32 v[106:107], v[106:107], v[110:111]
	v_pk_add_f32 v[116:117], v[116:117], 1.0 op_sel_hi:[1,0]
	v_pk_mul_f32 v[110:111], v[112:113], v[172:173] op_sel_hi:[1,0]
	v_rcp_f32_e32 v116, v116
	v_rcp_f32_e32 v117, v117
	v_pk_add_f32 v[112:113], v[120:121], 1.0 op_sel_hi:[1,0]
	v_pk_mul_f32 v[98:99], v[98:99], v[172:173] op_sel_hi:[1,0]
	v_rcp_f32_e32 v112, v112
	v_rcp_f32_e32 v113, v113
	v_pk_mul_f32 v[106:107], v[106:107], v[116:117]
	v_pk_mul_f32 v[116:117], v[98:99], s[10:11] op_sel_hi:[1,0]
	v_pk_mul_f32 v[108:109], v[108:109], v[110:111]
	v_exp_f32_e32 v116, v116
	v_exp_f32_e32 v117, v117
	v_pk_mul_f32 v[100:101], v[100:101], v[172:173] op_sel_hi:[1,0]
	v_pk_mul_f32 v[108:109], v[108:109], v[112:113]
	v_pk_mul_f32 v[112:113], v[100:101], s[10:11] op_sel_hi:[1,0]
	v_pk_mul_f32 v[102:103], v[102:103], v[172:173] op_sel_hi:[1,0]
	v_exp_f32_e32 v112, v112
	v_exp_f32_e32 v113, v113
	v_pk_add_f32 v[110:111], v[116:117], 1.0 op_sel_hi:[1,0]
	v_pk_mul_f32 v[98:99], v[98:99], v[102:103]
	v_rcp_f32_e32 v102, v110
	v_rcp_f32_e32 v103, v111
	v_pk_add_f32 v[110:111], v[112:113], 1.0 op_sel_hi:[1,0]
	v_mad_i64_i32 v[118:119], s[22:23], v166, s46, v[148:149]
	v_rcp_f32_e32 v110, v110
	v_rcp_f32_e32 v111, v111
	v_pk_mul_f32 v[102:103], v[98:99], v[102:103]
	v_pk_mul_f32 v[98:99], v[104:105], v[172:173] op_sel_hi:[1,0]
	v_pk_mul_f32 v[90:91], v[90:91], v[162:163] op_sel_hi:[1,0]
	v_pk_mul_f32 v[98:99], v[100:101], v[98:99]
	v_pk_mul_f32 v[92:93], v[92:93], v[162:163] op_sel_hi:[1,0]
	v_pk_mul_f32 v[104:105], v[98:99], v[110:111]
	v_lshl_add_u64 v[110:111], v[118:119], 0, v[114:115]
	v_cvt_pk_bf16_f32 v98, v106, v107
	v_cvt_pk_bf16_f32 v99, v108, v109
	v_cvt_pk_bf16_f32 v100, v102, v103
	v_cvt_pk_bf16_f32 v101, v104, v105
	global_store_dwordx4 v[110:111], v[98:101], off nt
	v_pk_mul_f32 v[102:103], v[92:93], s[10:11] op_sel_hi:[1,0]
	v_pk_mul_f32 v[94:95], v[94:95], v[162:163] op_sel_hi:[1,0]
	v_pk_mul_f32 v[98:99], v[90:91], s[10:11] op_sel_hi:[1,0]
	v_exp_f32_e32 v102, v102
	v_exp_f32_e32 v98, v98
	v_exp_f32_e32 v99, v99
	v_exp_f32_e32 v103, v103
	v_pk_mul_f32 v[90:91], v[90:91], v[94:95]
	v_pk_mul_f32 v[94:95], v[96:97], v[162:163] op_sel_hi:[1,0]
	v_pk_add_f32 v[98:99], v[98:99], 1.0 op_sel_hi:[1,0]
	v_pk_add_f32 v[96:97], v[102:103], 1.0 op_sel_hi:[1,0]
	v_rcp_f32_e32 v98, v98
	v_rcp_f32_e32 v99, v99
	v_rcp_f32_e32 v96, v96
	v_rcp_f32_e32 v97, v97
	v_pk_mul_f32 v[82:83], v[82:83], v[162:163] op_sel_hi:[1,0]
	v_pk_mul_f32 v[90:91], v[90:91], v[98:99]
	v_pk_mul_f32 v[98:99], v[82:83], s[10:11] op_sel_hi:[1,0]
	v_pk_mul_f32 v[92:93], v[92:93], v[94:95]
	v_exp_f32_e32 v98, v98
	v_exp_f32_e32 v99, v99
	v_pk_mul_f32 v[84:85], v[84:85], v[162:163] op_sel_hi:[1,0]
	v_pk_mul_f32 v[92:93], v[92:93], v[96:97]
	v_pk_mul_f32 v[96:97], v[84:85], s[10:11] op_sel_hi:[1,0]
	v_pk_mul_f32 v[86:87], v[86:87], v[162:163] op_sel_hi:[1,0]
	v_exp_f32_e32 v96, v96
	v_exp_f32_e32 v97, v97
	v_pk_add_f32 v[94:95], v[98:99], 1.0 op_sel_hi:[1,0]
	v_pk_mul_f32 v[82:83], v[82:83], v[86:87]
	v_rcp_f32_e32 v86, v94
	v_rcp_f32_e32 v87, v95
	v_pk_add_f32 v[94:95], v[96:97], 1.0 op_sel_hi:[1,0]
	v_rsq_f32_e32 v158, v158
	v_rcp_f32_e32 v94, v94
	v_rcp_f32_e32 v95, v95
	v_pk_mul_f32 v[86:87], v[82:83], v[86:87]
	v_pk_mul_f32 v[82:83], v[88:89], v[162:163] op_sel_hi:[1,0]
	v_mad_i64_i32 v[100:101], s[22:23], v160, s46, v[148:149]
	v_pk_mul_f32 v[82:83], v[84:85], v[82:83]
	v_pk_mul_f32 v[74:75], v[74:75], v[158:159] op_sel_hi:[1,0]
	v_pk_mul_f32 v[88:89], v[82:83], v[94:95]
	v_lshl_add_u64 v[94:95], v[100:101], 0, v[114:115]
	v_cvt_pk_bf16_f32 v82, v90, v91
	v_cvt_pk_bf16_f32 v83, v92, v93
	v_cvt_pk_bf16_f32 v84, v86, v87
	v_cvt_pk_bf16_f32 v85, v88, v89
	global_store_dwordx4 v[94:95], v[82:85], off nt
	v_pk_mul_f32 v[76:77], v[76:77], v[158:159] op_sel_hi:[1,0]
	v_pk_mul_f32 v[78:79], v[78:79], v[158:159] op_sel_hi:[1,0]
	v_pk_mul_f32 v[82:83], v[74:75], s[10:11] op_sel_hi:[1,0]
	v_pk_mul_f32 v[86:87], v[76:77], s[10:11] op_sel_hi:[1,0]
	v_exp_f32_e32 v82, v82
	v_exp_f32_e32 v83, v83
	v_exp_f32_e32 v86, v86
	v_exp_f32_e32 v87, v87
	v_pk_mul_f32 v[74:75], v[74:75], v[78:79]
	v_pk_add_f32 v[82:83], v[82:83], 1.0 op_sel_hi:[1,0]
	v_pk_mul_f32 v[78:79], v[80:81], v[158:159] op_sel_hi:[1,0]
	v_rcp_f32_e32 v82, v82
	v_rcp_f32_e32 v83, v83
	v_pk_add_f32 v[80:81], v[86:87], 1.0 op_sel_hi:[1,0]
	v_pk_mul_f32 v[62:63], v[62:63], v[158:159] op_sel_hi:[1,0]
	v_rcp_f32_e32 v80, v80
	v_rcp_f32_e32 v81, v81
	v_pk_mul_f32 v[74:75], v[74:75], v[82:83]
	v_pk_mul_f32 v[82:83], v[62:63], s[10:11] op_sel_hi:[1,0]
	v_pk_mul_f32 v[76:77], v[76:77], v[78:79]
	v_exp_f32_e32 v82, v82
	v_exp_f32_e32 v83, v83
	v_pk_mul_f32 v[64:65], v[64:65], v[158:159] op_sel_hi:[1,0]
	v_pk_mul_f32 v[76:77], v[76:77], v[80:81]
	v_pk_mul_f32 v[80:81], v[64:65], s[10:11] op_sel_hi:[1,0]
	v_pk_mul_f32 v[70:71], v[70:71], v[158:159] op_sel_hi:[1,0]
	v_exp_f32_e32 v80, v80
	v_exp_f32_e32 v81, v81
	v_pk_add_f32 v[78:79], v[82:83], 1.0 op_sel_hi:[1,0]
	v_pk_mul_f32 v[62:63], v[62:63], v[70:71]
	v_rcp_f32_e32 v70, v78
	v_rcp_f32_e32 v71, v79
; __device__ __forceinline__ unsigned cvt_pk_bf16(float lo, float hi) { unsigned r; asm volatile("v_cvt_pk_bf16_f32 %0, %1, %2" : "=v"(r) : "v"(lo), "v"(hi)); return r; }
; __device__ __forceinline__ unsigned cvt_pk_bf16(float lo, float hi) { unsigned r; asm volatile("v_cvt_pk_bf16_f32 %0, %1, %2" : "=v"(r) : "v"(lo), "v"(hi)); return r; }
;     __device__ __forceinline__ void operator()(const f32x4 (&acc)[2][2][4][2], const Unit& u, int wr, int wc, int fr, int fq) const {
;     ...
;         for (int ai = 0; ai < 2; ++ai)
; #pragma unroll
;             for (int m = 0; m < 4; ++m) { const int row = row0 + ai * HALF + m * 16; bf16_t* rowp = O + (size_t)row * ldc + col0; float a[8];
; #pragma unroll
;                 for (int n = 0; n < 2; ++n)
; #pragma unroll
;                     for (int i = 0; i < 4; i += 2) {
;                         const f32x2 r2 = {rs[ai][m], rs[ai][m]};
;                         const f32x2 g = (f32x2){acc[ai][0][m][n][i], acc[ai][0][m][n][i + 1]} * r2, up = (f32x2){acc[ai][1][m][n][i], acc[ai][1][m][n][i + 1]} * r2;
;                         const f32x2 t = g * (f32x2){-1.4426950408889634f, -1.4426950408889634f};
;                         const f32x2 d = (f32x2){__builtin_amdgcn_exp2f(t.x), __builtin_amdgcn_exp2f(t.y)} + (f32x2){1.0f, 1.0f};
;                         const f32x2 o2 = (g * up) * (f32x2){__builtin_amdgcn_rcpf(d.x), __builtin_amdgcn_rcpf(d.y)};
;                         a[4 * n + i] = o2.x; a[4 * n + i + 1] = o2.y; }
;                 u32x4 w; w.x = cvt_pk_bf16(a[0], a[1]); w.y = cvt_pk_bf16(a[2], a[3]); w.z = cvt_pk_bf16(a[4], a[5]); w.w = cvt_pk_bf16(a[6], a[7]);
;                 *(u32x4*)rowp = w; }
	v_pk_add_f32 v[78:79], v[80:81], 1.0 op_sel_hi:[1,0]
	v_mad_i64_i32 v[84:85], s[22:23], v156, s46, v[148:149]
	v_rcp_f32_e32 v78, v78
	v_rcp_f32_e32 v79, v79
	v_pk_mul_f32 v[70:71], v[62:63], v[70:71]
	v_pk_mul_f32 v[62:63], v[72:73], v[158:159] op_sel_hi:[1,0]
	v_pk_mul_f32 v[58:59], v[58:59], v[154:155] op_sel_hi:[1,0]
	v_pk_mul_f32 v[62:63], v[64:65], v[62:63]
	v_pk_mul_f32 v[60:61], v[60:61], v[154:155] op_sel_hi:[1,0]
	v_pk_mul_f32 v[72:73], v[62:63], v[78:79]
	v_lshl_add_u64 v[78:79], v[84:85], 0, v[114:115]
	v_cvt_pk_bf16_f32 v62, v74, v75
	v_cvt_pk_bf16_f32 v63, v76, v77
	v_cvt_pk_bf16_f32 v64, v70, v71
	v_cvt_pk_bf16_f32 v65, v72, v73
	global_store_dwordx4 v[78:79], v[62:65], off nt
	v_pk_mul_f32 v[70:71], v[60:61], s[10:11] op_sel_hi:[1,0]
	v_pk_mul_f32 v[66:67], v[66:67], v[154:155] op_sel_hi:[1,0]
	v_pk_mul_f32 v[62:63], v[58:59], s[10:11] op_sel_hi:[1,0]
	v_exp_f32_e32 v70, v70
	v_exp_f32_e32 v62, v62
	v_exp_f32_e32 v63, v63
	v_exp_f32_e32 v71, v71
	v_pk_mul_f32 v[58:59], v[58:59], v[66:67]
	v_pk_mul_f32 v[50:51], v[50:51], v[154:155] op_sel_hi:[1,0]
	v_pk_add_f32 v[62:63], v[62:63], 1.0 op_sel_hi:[1,0]
	v_pk_add_f32 v[66:67], v[70:71], 1.0 op_sel_hi:[1,0]
	v_rcp_f32_e32 v62, v62
	v_rcp_f32_e32 v63, v63
	v_rcp_f32_e32 v66, v66
	v_rcp_f32_e32 v67, v67
	v_pk_mul_f32 v[52:53], v[52:53], v[154:155] op_sel_hi:[1,0]
	v_pk_mul_f32 v[58:59], v[58:59], v[62:63]
	v_pk_mul_f32 v[62:63], v[68:69], v[154:155] op_sel_hi:[1,0]
	v_pk_mul_f32 v[68:69], v[50:51], s[10:11] op_sel_hi:[1,0]
	v_pk_mul_f32 v[60:61], v[60:61], v[62:63]
	v_exp_f32_e32 v68, v68
	v_exp_f32_e32 v69, v69
	v_pk_mul_f32 v[60:61], v[60:61], v[66:67]
	v_pk_mul_f32 v[66:67], v[52:53], s[10:11] op_sel_hi:[1,0]
	v_pk_mul_f32 v[54:55], v[54:55], v[154:155] op_sel_hi:[1,0]
	v_exp_f32_e32 v66, v66
	v_exp_f32_e32 v67, v67
	v_pk_add_f32 v[62:63], v[68:69], 1.0 op_sel_hi:[1,0]
	v_pk_mul_f32 v[50:51], v[50:51], v[54:55]
	v_rcp_f32_e32 v54, v62
	v_rcp_f32_e32 v55, v63
	v_fmamk_f32 v152, v152, 0x2d800000, v159
	v_pk_add_f32 v[62:63], v[66:67], 1.0 op_sel_hi:[1,0]
	v_rsq_f32_e32 v152, v152
	v_rcp_f32_e32 v62, v62
	v_rcp_f32_e32 v63, v63
	v_pk_mul_f32 v[54:55], v[50:51], v[54:55]
	v_pk_mul_f32 v[50:51], v[56:57], v[154:155] op_sel_hi:[1,0]
	v_mad_i64_i32 v[64:65], s[22:23], v165, s46, v[148:149]
	v_pk_mul_f32 v[50:51], v[52:53], v[50:51]
	v_pk_mul_f32 v[42:43], v[42:43], v[152:153] op_sel_hi:[1,0]
	v_pk_mul_f32 v[56:57], v[50:51], v[62:63]
	v_lshl_add_u64 v[62:63], v[64:65], 0, v[114:115]
	v_cvt_pk_bf16_f32 v50, v58, v59
	v_cvt_pk_bf16_f32 v51, v60, v61
	v_cvt_pk_bf16_f32 v52, v54, v55
	v_cvt_pk_bf16_f32 v53, v56, v57
	global_store_dwordx4 v[62:63], v[50:53], off nt
	v_pk_mul_f32 v[44:45], v[44:45], v[152:153] op_sel_hi:[1,0]
	v_pk_mul_f32 v[46:47], v[46:47], v[152:153] op_sel_hi:[1,0]
	v_pk_mul_f32 v[50:51], v[42:43], s[10:11] op_sel_hi:[1,0]
	v_pk_mul_f32 v[54:55], v[44:45], s[10:11] op_sel_hi:[1,0]
	v_exp_f32_e32 v50, v50
	v_exp_f32_e32 v51, v51
	v_exp_f32_e32 v54, v54
	v_exp_f32_e32 v55, v55
	v_pk_mul_f32 v[42:43], v[42:43], v[46:47]
	v_pk_add_f32 v[50:51], v[50:51], 1.0 op_sel_hi:[1,0]
	v_pk_mul_f32 v[46:47], v[48:49], v[152:153] op_sel_hi:[1,0]
	v_rcp_f32_e32 v50, v50
	v_rcp_f32_e32 v51, v51
	v_pk_add_f32 v[48:49], v[54:55], 1.0 op_sel_hi:[1,0]
	v_pk_mul_f32 v[34:35], v[34:35], v[152:153] op_sel_hi:[1,0]
	v_rcp_f32_e32 v48, v48
	v_rcp_f32_e32 v49, v49
	v_pk_mul_f32 v[42:43], v[42:43], v[50:51]
	v_pk_mul_f32 v[50:51], v[34:35], s[10:11] op_sel_hi:[1,0]
	v_pk_mul_f32 v[44:45], v[44:45], v[46:47]
	v_exp_f32_e32 v50, v50
	v_exp_f32_e32 v51, v51
	v_pk_mul_f32 v[36:37], v[36:37], v[152:153] op_sel_hi:[1,0]
	v_pk_mul_f32 v[44:45], v[44:45], v[48:49]
	v_pk_mul_f32 v[48:49], v[36:37], s[10:11] op_sel_hi:[1,0]
	v_pk_mul_f32 v[38:39], v[38:39], v[152:153] op_sel_hi:[1,0]
	v_exp_f32_e32 v48, v48
	v_exp_f32_e32 v49, v49
	v_pk_add_f32 v[46:47], v[50:51], 1.0 op_sel_hi:[1,0]
	v_pk_mul_f32 v[34:35], v[34:35], v[38:39]
	v_rcp_f32_e32 v38, v46
	v_rcp_f32_e32 v39, v47
	v_pk_add_f32 v[46:47], v[48:49], 1.0 op_sel_hi:[1,0]
	v_mad_i64_i32 v[52:53], s[22:23], v163, s46, v[148:149]
	v_rcp_f32_e32 v46, v46
	v_rcp_f32_e32 v47, v47
	v_pk_mul_f32 v[38:39], v[34:35], v[38:39]
	v_pk_mul_f32 v[34:35], v[40:41], v[152:153] op_sel_hi:[1,0]
	v_pk_mul_f32 v[26:27], v[26:27], v[150:151] op_sel_hi:[1,0]
	v_pk_mul_f32 v[34:35], v[36:37], v[34:35]
	v_pk_mul_f32 v[28:29], v[28:29], v[150:151] op_sel_hi:[1,0]
	v_pk_mul_f32 v[40:41], v[34:35], v[46:47]
	v_lshl_add_u64 v[46:47], v[52:53], 0, v[114:115]
	v_cvt_pk_bf16_f32 v34, v42, v43
	v_cvt_pk_bf16_f32 v35, v44, v45
	v_cvt_pk_bf16_f32 v36, v38, v39
	v_cvt_pk_bf16_f32 v37, v40, v41
	global_store_dwordx4 v[46:47], v[34:37], off nt
	v_pk_mul_f32 v[38:39], v[28:29], s[10:11] op_sel_hi:[1,0]
	v_pk_mul_f32 v[30:31], v[30:31], v[150:151] op_sel_hi:[1,0]
	v_pk_mul_f32 v[34:35], v[26:27], s[10:11] op_sel_hi:[1,0]
	v_exp_f32_e32 v38, v38
	v_exp_f32_e32 v34, v34
	v_exp_f32_e32 v35, v35
	v_exp_f32_e32 v39, v39
	v_pk_mul_f32 v[26:27], v[26:27], v[30:31]
	v_pk_mul_f32 v[30:31], v[32:33], v[150:151] op_sel_hi:[1,0]
; __device__ __forceinline__ unsigned cvt_pk_bf16(float lo, float hi) { unsigned r; asm volatile("v_cvt_pk_bf16_f32 %0, %1, %2" : "=v"(r) : "v"(lo), "v"(hi)); return r; }
; __device__ __forceinline__ unsigned cvt_pk_bf16(float lo, float hi) { unsigned r; asm volatile("v_cvt_pk_bf16_f32 %0, %1, %2" : "=v"(r) : "v"(lo), "v"(hi)); return r; }
; #define PG8_BAR __builtin_amdgcn_s_barrier()
;     __device__ __forceinline__ void operator()(const f32x4 (&acc)[2][2][4][2], const Unit& u, int wr, int wc, int fr, int fq) const {
;     ...
;         for (int ai = 0; ai < 2; ++ai)
; #pragma unroll
;             for (int m = 0; m < 4; ++m) { const int row = row0 + ai * HALF + m * 16; bf16_t* rowp = O + (size_t)row * ldc + col0; float a[8];
; #pragma unroll
;                 for (int n = 0; n < 2; ++n)
; #pragma unroll
;                     for (int i = 0; i < 4; i += 2) {
;                         const f32x2 r2 = {rs[ai][m], rs[ai][m]};
;                         const f32x2 g = (f32x2){acc[ai][0][m][n][i], acc[ai][0][m][n][i + 1]} * r2, up = (f32x2){acc[ai][1][m][n][i], acc[ai][1][m][n][i + 1]} * r2;
;                         const f32x2 t = g * (f32x2){-1.4426950408889634f, -1.4426950408889634f};
;                         const f32x2 d = (f32x2){__builtin_amdgcn_exp2f(t.x), __builtin_amdgcn_exp2f(t.y)} + (f32x2){1.0f, 1.0f};
;                         const f32x2 o2 = (g * up) * (f32x2){__builtin_amdgcn_rcpf(d.x), __builtin_amdgcn_rcpf(d.y)};
;                         a[4 * n + i] = o2.x; a[4 * n + i + 1] = o2.y; }
;                 u32x4 w; w.x = cvt_pk_bf16(a[0], a[1]); w.y = cvt_pk_bf16(a[2], a[3]); w.z = cvt_pk_bf16(a[4], a[5]); w.w = cvt_pk_bf16(a[6], a[7]);
;                 *(u32x4*)rowp = w; }
; template <class Epi, class Sched, bool ALIGN_EPI = false, bool SP2 = false>
; __device__ __forceinline__ void gemm_phase(PG8_LAS unsigned char* lds, const Gemm g, const Sched& S, const Epi& E) {
;     ...
; #pragma unroll
;         for (int a = 0; a < 2; ++a)
; #pragma unroll
;             for (int b = 0; b < 2; ++b)
; #pragma unroll
;                 for (int m = 0; m < 4; ++m)
; #pragma unroll
;                     for (int n = 0; n < 2; ++n) { d64x2 z_; asm volatile("v_mov_b64 %0, 0\n\tv_mov_b64 %1, 0" : "=v"(z_.x), "=v"(z_.y)); acc[a][b][m][n] = __builtin_bit_cast(f32x4, z_); }
;         cur = nxt; cA = nA; cB = nB; ++ui;
;         if constexpr (ALIGN_EPI) { if (wr == 1) PG8_BAR; }
	v_pk_add_f32 v[34:35], v[34:35], 1.0 op_sel_hi:[1,0]
	v_pk_add_f32 v[32:33], v[38:39], 1.0 op_sel_hi:[1,0]
	v_rcp_f32_e32 v34, v34
	v_rcp_f32_e32 v35, v35
	v_rcp_f32_e32 v32, v32
	v_rcp_f32_e32 v33, v33
	v_pk_mul_f32 v[18:19], v[18:19], v[150:151] op_sel_hi:[1,0]
	v_pk_mul_f32 v[26:27], v[26:27], v[34:35]
	v_pk_mul_f32 v[34:35], v[18:19], s[10:11] op_sel_hi:[1,0]
	v_pk_mul_f32 v[28:29], v[28:29], v[30:31]
	v_exp_f32_e32 v34, v34
	v_exp_f32_e32 v35, v35
	v_pk_mul_f32 v[20:21], v[20:21], v[150:151] op_sel_hi:[1,0]
	v_pk_mul_f32 v[28:29], v[28:29], v[32:33]
	v_pk_mul_f32 v[32:33], v[20:21], s[10:11] op_sel_hi:[1,0]
	v_pk_mul_f32 v[22:23], v[22:23], v[150:151] op_sel_hi:[1,0]
	v_exp_f32_e32 v32, v32
	v_exp_f32_e32 v33, v33
	v_pk_add_f32 v[30:31], v[34:35], 1.0 op_sel_hi:[1,0]
	v_pk_mul_f32 v[18:19], v[18:19], v[22:23]
	v_rcp_f32_e32 v22, v30
	v_rcp_f32_e32 v23, v31
	v_fmamk_f32 v146, v146, 0x2d800000, v159
	v_pk_add_f32 v[30:31], v[32:33], 1.0 op_sel_hi:[1,0]
	v_rsq_f32_e32 v146, v146
	v_rcp_f32_e32 v30, v30
	v_rcp_f32_e32 v31, v31
	v_pk_mul_f32 v[22:23], v[18:19], v[22:23]
	v_pk_mul_f32 v[18:19], v[24:25], v[150:151] op_sel_hi:[1,0]
	v_mad_i64_i32 v[36:37], s[22:23], v161, s46, v[148:149]
	v_pk_mul_f32 v[18:19], v[20:21], v[18:19]
	v_pk_mul_f32 v[10:11], v[10:11], v[146:147] op_sel_hi:[1,0]
	v_pk_mul_f32 v[24:25], v[18:19], v[30:31]
	v_lshl_add_u64 v[30:31], v[36:37], 0, v[114:115]
	v_cvt_pk_bf16_f32 v18, v26, v27
	v_cvt_pk_bf16_f32 v19, v28, v29
	v_cvt_pk_bf16_f32 v20, v22, v23
	v_cvt_pk_bf16_f32 v21, v24, v25
	global_store_dwordx4 v[30:31], v[18:21], off nt
	v_pk_mul_f32 v[12:13], v[12:13], v[146:147] op_sel_hi:[1,0]
	v_pk_mul_f32 v[14:15], v[14:15], v[146:147] op_sel_hi:[1,0]
	v_pk_mul_f32 v[18:19], v[10:11], s[10:11] op_sel_hi:[1,0]
	v_pk_mul_f32 v[22:23], v[12:13], s[10:11] op_sel_hi:[1,0]
	v_exp_f32_e32 v18, v18
	v_exp_f32_e32 v19, v19
	v_exp_f32_e32 v22, v22
	v_exp_f32_e32 v23, v23
	v_pk_mul_f32 v[10:11], v[10:11], v[14:15]
	v_pk_add_f32 v[18:19], v[18:19], 1.0 op_sel_hi:[1,0]
	v_pk_mul_f32 v[14:15], v[16:17], v[146:147] op_sel_hi:[1,0]
	v_rcp_f32_e32 v18, v18
	v_rcp_f32_e32 v19, v19
	v_pk_add_f32 v[16:17], v[22:23], 1.0 op_sel_hi:[1,0]
	v_pk_mul_f32 v[2:3], v[2:3], v[146:147] op_sel_hi:[1,0]
	v_rcp_f32_e32 v16, v16
	v_rcp_f32_e32 v17, v17
	v_pk_mul_f32 v[10:11], v[10:11], v[18:19]
	v_pk_mul_f32 v[18:19], v[2:3], s[10:11] op_sel_hi:[1,0]
	v_pk_mul_f32 v[12:13], v[12:13], v[14:15]
	v_exp_f32_e32 v18, v18
	v_exp_f32_e32 v19, v19
	v_pk_mul_f32 v[4:5], v[4:5], v[146:147] op_sel_hi:[1,0]
	v_pk_mul_f32 v[12:13], v[12:13], v[16:17]
	v_pk_mul_f32 v[16:17], v[4:5], s[10:11] op_sel_hi:[1,0]
	v_pk_mul_f32 v[6:7], v[6:7], v[146:147] op_sel_hi:[1,0]
	v_exp_f32_e32 v16, v16
	v_exp_f32_e32 v17, v17
	v_pk_add_f32 v[14:15], v[18:19], 1.0 op_sel_hi:[1,0]
	v_pk_mul_f32 v[2:3], v[2:3], v[6:7]
	v_rcp_f32_e32 v6, v14
	v_rcp_f32_e32 v7, v15
	v_pk_add_f32 v[14:15], v[16:17], 1.0 op_sel_hi:[1,0]
	v_mad_i64_i32 v[20:21], s[22:23], v157, s46, v[148:149]
	v_rcp_f32_e32 v14, v14
	v_rcp_f32_e32 v15, v15
	v_pk_mul_f32 v[6:7], v[2:3], v[6:7]
	v_pk_mul_f32 v[2:3], v[8:9], v[146:147] op_sel_hi:[1,0]
	s_nop 0
	v_pk_mul_f32 v[2:3], v[4:5], v[2:3]
	s_nop 0
	v_pk_mul_f32 v[8:9], v[2:3], v[14:15]
	v_lshl_add_u64 v[14:15], v[20:21], 0, v[114:115]
	v_cvt_pk_bf16_f32 v2, v10, v11
	v_cvt_pk_bf16_f32 v3, v12, v13
	v_cvt_pk_bf16_f32 v4, v6, v7
	v_cvt_pk_bf16_f32 v5, v8, v9
	global_store_dwordx4 v[14:15], v[2:5], off nt
	s_cbranch_vccnz .LBB0_1677
	s_andn2_b64 vcc, exec, s[2:3]
	v_mov_b64 v[122:123], 0
	v_mov_b64 v[124:125], 0
	v_mov_b64 v[114:115], 0
	v_mov_b64 v[116:117], 0
	v_mov_b64 v[106:107], 0
	v_mov_b64 v[108:109], 0
	v_mov_b64 v[98:99], 0
	v_mov_b64 v[100:101], 0
	v_mov_b64 v[90:91], 0
	v_mov_b64 v[92:93], 0
	v_mov_b64 v[82:83], 0
	v_mov_b64 v[84:85], 0
	v_mov_b64 v[74:75], 0
	v_mov_b64 v[76:77], 0
	v_mov_b64 v[62:63], 0
	v_mov_b64 v[64:65], 0
	v_mov_b64 v[126:127], 0
	v_mov_b64 v[128:129], 0
	v_mov_b64 v[118:119], 0
	v_mov_b64 v[120:121], 0
	v_mov_b64 v[110:111], 0
	v_mov_b64 v[112:113], 0
	v_mov_b64 v[102:103], 0
	v_mov_b64 v[104:105], 0
	v_mov_b64 v[94:95], 0
	v_mov_b64 v[96:97], 0
	v_mov_b64 v[86:87], 0
	v_mov_b64 v[88:89], 0
	v_mov_b64 v[78:79], 0
	v_mov_b64 v[80:81], 0
	v_mov_b64 v[70:71], 0
	v_mov_b64 v[72:73], 0
	v_mov_b64 v[58:59], 0
	v_mov_b64 v[60:61], 0
	v_mov_b64 v[50:51], 0
	v_mov_b64 v[52:53], 0
	v_mov_b64 v[42:43], 0
	v_mov_b64 v[44:45], 0
	v_mov_b64 v[34:35], 0
	v_mov_b64 v[36:37], 0
	v_mov_b64 v[26:27], 0
	v_mov_b64 v[28:29], 0
	v_mov_b64 v[18:19], 0
	v_mov_b64 v[20:21], 0
	v_mov_b64 v[10:11], 0
	v_mov_b64 v[12:13], 0
	v_mov_b64 v[2:3], 0
	v_mov_b64 v[4:5], 0
	v_mov_b64 v[66:67], 0
	v_mov_b64 v[68:69], 0
	v_mov_b64 v[54:55], 0
	v_mov_b64 v[56:57], 0
	v_mov_b64 v[46:47], 0
	v_mov_b64 v[48:49], 0
	v_mov_b64 v[38:39], 0
	v_mov_b64 v[40:41], 0
	v_mov_b64 v[30:31], 0
	v_mov_b64 v[32:33], 0
	v_mov_b64 v[22:23], 0
	v_mov_b64 v[24:25], 0
	v_mov_b64 v[14:15], 0
	v_mov_b64 v[16:17], 0
	v_mov_b64 v[6:7], 0
	v_mov_b64 v[8:9], 0
	s_cbranch_vccnz .LBB0_1676
	s_barrier
	s_branch .LBB0_1676
